# norm2 phase hand-written: wave per row, two rows in flight, all loads of a row issued together, DPP reduction (same f32 formula)
# baseline (speedup 1.0000x reference)
; DEV int tidx() { return tidx_full() & 255; }
; #define VBID ((int)blockIdx.x * 2 + vhalf())
; DEV void phase_norm_adaln(const float* __restrict__ X, const float* __restrict__ gvec, const float* __restrict__ mod,
;                           int bg0, int L, int sh_off, int sc_off, u16* __restrict__ H) {
;   const int tid = tidx();
;   const int wave = tid >> 6, lane = tid & 63;
;   constexpr int RB = 4;
;   const int stride = NVB * 4;
;   for (int row0 = VBID * 4 + wave; row0 < NTOK; row0 += stride * RB) {
;     float4 v[RB][4];
;     float ss[RB];
; #pragma unroll
;     for (int j = 0; j < RB; ++j) {
;       const int row = row0 + j * stride;
;       const float* x = X + (long)(row < NTOK ? row : row0) * D;
; #pragma unroll
;       for (int i = 0; i < 4; ++i) v[j][i] = *(const float4*)(x + lane * 4 + 256 * i);
;     }
; #pragma unroll
;     for (int j = 0; j < RB; ++j) {
;       float t = 0.f;
; #pragma unroll
;       for (int i = 0; i < 4; ++i) t += v[j][i].x * v[j][i].x + v[j][i].y * v[j][i].y + v[j][i].z * v[j][i].z + v[j][i].w * v[j][i].w;
;       ss[j] = wave_sum(t);
;     }
; #pragma unroll
;     for (int j = 0; j < RB; ++j) {
;       const int row = row0 + j * stride;
;       if (row < NTOK) {
;         const float rstd = rsqrtf(ss[j] * (1.f / 1024.f) + EPSF);
;         const float* mrow = mod + (long)(bg0 + row / L) * DIN;
; #pragma unroll
;         for (int i = 0; i < 4; ++i) {
;           const int k = lane * 4 + 256 * i;
;           const float4 g = *(const float4*)(gvec + k);
;           const float4 sc = *(const float4*)(mrow + sc_off + k);
;           const float4 sh = *(const float4*)(mrow + sh_off + k);
;           const float o0 = v[j][i].x * rstd * g.x * (1.f + sc.x) + sh.x;
;           const float o1 = v[j][i].y * rstd * g.y * (1.f + sc.y) + sh.y;
;           const float o2 = v[j][i].z * rstd * g.z * (1.f + sc.z) + sh.z;
;           const float o3 = v[j][i].w * rstd * g.w * (1.f + sc.w) + sh.w;
;           *(uint2*)(H + (long)row * D + k) = make_uint2(pack2(o0, o1), pack2(o2, o3));
;         }
;       }
;     }
;   }
; }
.LBB0_1052:
	s_or_b64 exec, exec, s[0:1]
	v_readfirstlane_b32 s0, v202
	s_lshr_b32 s0, s0, 6
	v_mov_b32_e32 v5, v202
	s_and_b32 s0, s0, 0x3fffffc
	s_waitcnt lgkmcnt(0)
	s_barrier
	s_mov_b64 s[2:3], exec
	v_readfirstlane_b32 s37, v202
	v_readlane_b32 s36, v252, 18
	v_readlane_b32 s38, v249, 30
	v_readlane_b32 s39, v249, 31
	v_readlane_b32 s40, v249, 48
	v_readlane_b32 s41, v249, 49
	s_lshr_b32 s37, s37, 6
	s_lshl_b32 s14, s81, 2
	s_add_u32 s14, s14, s37
	v_and_b32_e32 v115, 63, v202
	v_lshlrev_b32_e32 v116, 3, v115
	v_lshlrev_b32_e32 v115, 4, v115
	global_load_dwordx4 v[96:99], v115, s[38:39]
	global_load_dwordx4 v[100:103], v115, s[38:39] offset:1024
	global_load_dwordx4 v[104:107], v115, s[38:39] offset:2048
	global_load_dwordx4 v[108:111], v115, s[38:39] offset:3072
	s_lshl_b32 s15, s14, 11
	s_add_u32 s8, s40, s15
	s_addc_u32 s9, s41, 0
	s_lshl_b32 s15, s14, 12
	s_add_u32 s0, s64, s15
	s_addc_u32 s1, s65, 0
	s_lshr_b32 s15, s14, s36
	s_add_u32 s15, s15, s16
	s_mul_i32 s15, s15, 0x6000
	s_add_u32 s42, s86, s15
	s_addc_u32 s43, s87, 0
	s_add_u32 s4, s42, 0x4000
	s_addc_u32 s5, s43, 0
	s_add_u32 s6, s42, 0x3000
	s_addc_u32 s7, s43, 0
	global_load_dwordx4 v[0:3], v115, s[0:1]
	global_load_dwordx4 v[4:7], v115, s[0:1] offset:1024
	global_load_dwordx4 v[8:11], v115, s[0:1] offset:2048
	global_load_dwordx4 v[12:15], v115, s[0:1] offset:3072
	global_load_dwordx4 v[32:35], v115, s[4:5]
	global_load_dwordx4 v[36:39], v115, s[4:5] offset:1024
	global_load_dwordx4 v[40:43], v115, s[4:5] offset:2048
	global_load_dwordx4 v[44:47], v115, s[4:5] offset:3072
	global_load_dwordx4 v[48:51], v115, s[6:7]
	global_load_dwordx4 v[52:55], v115, s[6:7] offset:1024
	global_load_dwordx4 v[56:59], v115, s[6:7] offset:2048
	global_load_dwordx4 v[60:63], v115, s[6:7] offset:3072
	s_add_u32 s14, s14, 0x800
	s_lshl_b32 s15, s14, 12
	s_add_u32 s0, s64, s15
	s_addc_u32 s1, s65, 0
	s_lshr_b32 s15, s14, s36
	s_add_u32 s15, s15, s16
	s_mul_i32 s15, s15, 0x6000
	s_add_u32 s42, s86, s15
	s_addc_u32 s43, s87, 0
	s_add_u32 s4, s42, 0x4000
	s_addc_u32 s5, s43, 0
	s_add_u32 s6, s42, 0x3000
	s_addc_u32 s7, s43, 0
	global_load_dwordx4 v[16:19], v115, s[0:1]
	global_load_dwordx4 v[20:23], v115, s[0:1] offset:1024
	global_load_dwordx4 v[24:27], v115, s[0:1] offset:2048
	global_load_dwordx4 v[28:31], v115, s[0:1] offset:3072
	global_load_dwordx4 v[64:67], v115, s[4:5]
	global_load_dwordx4 v[68:71], v115, s[4:5] offset:1024
	global_load_dwordx4 v[72:75], v115, s[4:5] offset:2048
	global_load_dwordx4 v[76:79], v115, s[4:5] offset:3072
	global_load_dwordx4 v[80:83], v115, s[6:7]
	global_load_dwordx4 v[84:87], v115, s[6:7] offset:1024
	global_load_dwordx4 v[88:91], v115, s[6:7] offset:2048
	global_load_dwordx4 v[92:95], v115, s[6:7] offset:3072
	s_add_u32 s14, s14, 0x800
	s_mov_b32 s44, 0
.Lnorm2_loop:
	s_waitcnt vmcnt(12)
	v_mul_f32_e32 v112, v0, v0
	v_fmac_f32_e32 v112, v1, v1
	v_fmac_f32_e32 v112, v2, v2
	v_fmac_f32_e32 v112, v3, v3
	v_fmac_f32_e32 v112, v4, v4
	v_fmac_f32_e32 v112, v5, v5
	v_fmac_f32_e32 v112, v6, v6
	v_fmac_f32_e32 v112, v7, v7
	v_fmac_f32_e32 v112, v8, v8
	v_fmac_f32_e32 v112, v9, v9
	v_fmac_f32_e32 v112, v10, v10
	v_fmac_f32_e32 v112, v11, v11
	v_fmac_f32_e32 v112, v12, v12
	v_fmac_f32_e32 v112, v13, v13
	v_fmac_f32_e32 v112, v14, v14
	v_fmac_f32_e32 v112, v15, v15
	s_nop 1
	v_add_f32_dpp v112, v112, v112 quad_perm:[1,0,3,2] row_mask:0xf bank_mask:0xf
	s_nop 1
	v_add_f32_dpp v112, v112, v112 quad_perm:[2,3,0,1] row_mask:0xf bank_mask:0xf
	s_nop 1
	v_add_f32_dpp v112, v112, v112 row_half_mirror row_mask:0xf bank_mask:0xf
	s_nop 1
	v_add_f32_dpp v112, v112, v112 row_mirror row_mask:0xf bank_mask:0xf
	s_nop 1
	v_add_f32_dpp v112, v112, v112 row_bcast:15 row_mask:0xa bank_mask:0xf
	s_nop 1
	v_add_f32_dpp v112, v112, v112 row_bcast:31 row_mask:0xc bank_mask:0xf
	s_nop 1
	v_readlane_b32 s15, v112, 63
	v_mov_b32_e32 v113, 0x3a800000
	s_nop 1
	v_fma_f32 v117, s15, v113, v212
	v_cmp_gt_f32_e32 vcc, s25, v117
	v_mul_f32_e32 v114, 0x4b800000, v117
	v_cndmask_b32_e32 v117, v117, v114, vcc
	v_rsq_f32_e32 v117, v117
	s_nop 0
	v_mul_f32_e32 v114, 0x45800000, v117
	v_cndmask_b32_e32 v117, v117, v114, vcc
	v_mul_f32_e32 v0, v0, v117
	v_mul_f32_e32 v0, v96, v0
	v_add_f32_e32 v32, 1.0, v32
	v_fma_f32 v0, v0, v32, v48
	v_mul_f32_e32 v1, v1, v117
	v_mul_f32_e32 v1, v97, v1
	v_add_f32_e32 v33, 1.0, v33
	v_fma_f32 v1, v1, v33, v49
	v_mul_f32_e32 v2, v2, v117
	v_mul_f32_e32 v2, v98, v2
	v_add_f32_e32 v34, 1.0, v34
	v_fma_f32 v2, v2, v34, v50
	v_mul_f32_e32 v3, v3, v117
	v_mul_f32_e32 v3, v99, v3
	v_add_f32_e32 v35, 1.0, v35
	v_fma_f32 v3, v3, v35, v51
	v_mul_f32_e32 v4, v4, v117
	v_mul_f32_e32 v4, v100, v4
	v_add_f32_e32 v36, 1.0, v36
	v_fma_f32 v4, v4, v36, v52
	v_mul_f32_e32 v5, v5, v117
	v_mul_f32_e32 v5, v101, v5
	v_add_f32_e32 v37, 1.0, v37
	v_fma_f32 v5, v5, v37, v53
	v_mul_f32_e32 v6, v6, v117
	v_mul_f32_e32 v6, v102, v6
	v_add_f32_e32 v38, 1.0, v38
	v_fma_f32 v6, v6, v38, v54
	v_mul_f32_e32 v7, v7, v117
	v_mul_f32_e32 v7, v103, v7
	v_add_f32_e32 v39, 1.0, v39
	v_fma_f32 v7, v7, v39, v55
	v_mul_f32_e32 v8, v8, v117
	v_mul_f32_e32 v8, v104, v8
	v_add_f32_e32 v40, 1.0, v40
	v_fma_f32 v8, v8, v40, v56
	v_mul_f32_e32 v9, v9, v117
	v_mul_f32_e32 v9, v105, v9
	v_add_f32_e32 v41, 1.0, v41
	v_fma_f32 v9, v9, v41, v57
	v_mul_f32_e32 v10, v10, v117
	v_mul_f32_e32 v10, v106, v10
	v_add_f32_e32 v42, 1.0, v42
	v_fma_f32 v10, v10, v42, v58
	v_mul_f32_e32 v11, v11, v117
	v_mul_f32_e32 v11, v107, v11
	v_add_f32_e32 v43, 1.0, v43
	v_fma_f32 v11, v11, v43, v59
	v_mul_f32_e32 v12, v12, v117
	v_mul_f32_e32 v12, v108, v12
	v_add_f32_e32 v44, 1.0, v44
	v_fma_f32 v12, v12, v44, v60
	v_mul_f32_e32 v13, v13, v117
	v_mul_f32_e32 v13, v109, v13
	v_add_f32_e32 v45, 1.0, v45
	v_fma_f32 v13, v13, v45, v61
	v_mul_f32_e32 v14, v14, v117
	v_mul_f32_e32 v14, v110, v14
	v_add_f32_e32 v46, 1.0, v46
	v_fma_f32 v14, v14, v46, v62
	v_mul_f32_e32 v15, v15, v117
	v_mul_f32_e32 v15, v111, v15
	v_add_f32_e32 v47, 1.0, v47
	v_fma_f32 v15, v15, v47, v63
	v_cvt_pk_bf16_f32 v0, v0, v1
	v_cvt_pk_bf16_f32 v1, v2, v3
	global_store_dwordx2 v116, v[0:1], s[8:9]
	v_cvt_pk_bf16_f32 v4, v4, v5
	v_cvt_pk_bf16_f32 v5, v6, v7
	global_store_dwordx2 v116, v[4:5], s[8:9] offset:512
	v_cvt_pk_bf16_f32 v8, v8, v9
	v_cvt_pk_bf16_f32 v9, v10, v11
	global_store_dwordx2 v116, v[8:9], s[8:9] offset:1024
	v_cvt_pk_bf16_f32 v12, v12, v13
	v_cvt_pk_bf16_f32 v13, v14, v15
	global_store_dwordx2 v116, v[12:13], s[8:9] offset:1536
	s_add_u32 s8, s8, 0x400000
	s_addc_u32 s9, s9, 0
	s_cmp_eq_u32 s44, 7
	s_cbranch_scc1 .Lnorm2_tail
; #define VBID ((int)blockIdx.x * 2 + vhalf())
; DEV void phase_norm_adaln(const float* __restrict__ X, const float* __restrict__ gvec, const float* __restrict__ mod,
;                           int bg0, int L, int sh_off, int sc_off, u16* __restrict__ H) {
;     ...
;   for (int row0 = VBID * 4 + wave; row0 < NTOK; row0 += stride * RB) {
;     float4 v[RB][4];
;     float ss[RB];
; #pragma unroll
;     for (int j = 0; j < RB; ++j) {
;       const int row = row0 + j * stride;
;       const float* x = X + (long)(row < NTOK ? row : row0) * D;
; #pragma unroll
;       for (int i = 0; i < 4; ++i) v[j][i] = *(const float4*)(x + lane * 4 + 256 * i);
;     }
; #pragma unroll
;     for (int j = 0; j < RB; ++j) {
;       float t = 0.f;
; #pragma unroll
;       for (int i = 0; i < 4; ++i) t += v[j][i].x * v[j][i].x + v[j][i].y * v[j][i].y + v[j][i].z * v[j][i].z + v[j][i].w * v[j][i].w;
;       ss[j] = wave_sum(t);
;     }
; #pragma unroll
;     for (int j = 0; j < RB; ++j) {
;       const int row = row0 + j * stride;
;       if (row < NTOK) {
;         const float rstd = rsqrtf(ss[j] * (1.f / 1024.f) + EPSF);
;         const float* mrow = mod + (long)(bg0 + row / L) * DIN;
; #pragma unroll
;         for (int i = 0; i < 4; ++i) {
;           const int k = lane * 4 + 256 * i;
;           const float4 g = *(const float4*)(gvec + k);
;           const float4 sc = *(const float4*)(mrow + sc_off + k);
;           const float4 sh = *(const float4*)(mrow + sh_off + k);
;           const float o0 = v[j][i].x * rstd * g.x * (1.f + sc.x) + sh.x;
;           const float o1 = v[j][i].y * rstd * g.y * (1.f + sc.y) + sh.y;
;           const float o2 = v[j][i].z * rstd * g.z * (1.f + sc.z) + sh.z;
;           const float o3 = v[j][i].w * rstd * g.w * (1.f + sc.w) + sh.w;
;           *(uint2*)(H + (long)row * D + k) = make_uint2(pack2(o0, o1), pack2(o2, o3));
;         }
;       }
;     }
;   }
	s_lshl_b32 s15, s14, 12
	s_add_u32 s0, s64, s15
	s_addc_u32 s1, s65, 0
	s_lshr_b32 s15, s14, s36
	s_add_u32 s15, s15, s16
	s_mul_i32 s15, s15, 0x6000
	s_add_u32 s42, s86, s15
	s_addc_u32 s43, s87, 0
	s_add_u32 s4, s42, 0x4000
	s_addc_u32 s5, s43, 0
	s_add_u32 s6, s42, 0x3000
	s_addc_u32 s7, s43, 0
	global_load_dwordx4 v[0:3], v115, s[0:1]
	global_load_dwordx4 v[4:7], v115, s[0:1] offset:1024
	global_load_dwordx4 v[8:11], v115, s[0:1] offset:2048
	global_load_dwordx4 v[12:15], v115, s[0:1] offset:3072
	global_load_dwordx4 v[32:35], v115, s[4:5]
	global_load_dwordx4 v[36:39], v115, s[4:5] offset:1024
	global_load_dwordx4 v[40:43], v115, s[4:5] offset:2048
	global_load_dwordx4 v[44:47], v115, s[4:5] offset:3072
	global_load_dwordx4 v[48:51], v115, s[6:7]
	global_load_dwordx4 v[52:55], v115, s[6:7] offset:1024
	global_load_dwordx4 v[56:59], v115, s[6:7] offset:2048
	global_load_dwordx4 v[60:63], v115, s[6:7] offset:3072
	s_add_u32 s14, s14, 0x800
	s_waitcnt vmcnt(16)
	v_mul_f32_e32 v112, v16, v16
	v_fmac_f32_e32 v112, v17, v17
	v_fmac_f32_e32 v112, v18, v18
	v_fmac_f32_e32 v112, v19, v19
	v_fmac_f32_e32 v112, v20, v20
	v_fmac_f32_e32 v112, v21, v21
	v_fmac_f32_e32 v112, v22, v22
	v_fmac_f32_e32 v112, v23, v23
	v_fmac_f32_e32 v112, v24, v24
	v_fmac_f32_e32 v112, v25, v25
	v_fmac_f32_e32 v112, v26, v26
	v_fmac_f32_e32 v112, v27, v27
	v_fmac_f32_e32 v112, v28, v28
	v_fmac_f32_e32 v112, v29, v29
	v_fmac_f32_e32 v112, v30, v30
	v_fmac_f32_e32 v112, v31, v31
	s_nop 1
	v_add_f32_dpp v112, v112, v112 quad_perm:[1,0,3,2] row_mask:0xf bank_mask:0xf
	s_nop 1
	v_add_f32_dpp v112, v112, v112 quad_perm:[2,3,0,1] row_mask:0xf bank_mask:0xf
	s_nop 1
	v_add_f32_dpp v112, v112, v112 row_half_mirror row_mask:0xf bank_mask:0xf
	s_nop 1
	v_add_f32_dpp v112, v112, v112 row_mirror row_mask:0xf bank_mask:0xf
	s_nop 1
	v_add_f32_dpp v112, v112, v112 row_bcast:15 row_mask:0xa bank_mask:0xf
	s_nop 1
	v_add_f32_dpp v112, v112, v112 row_bcast:31 row_mask:0xc bank_mask:0xf
	s_nop 1
	v_readlane_b32 s15, v112, 63
	v_mov_b32_e32 v113, 0x3a800000
	s_nop 1
	v_fma_f32 v117, s15, v113, v212
	v_cmp_gt_f32_e32 vcc, s25, v117
	v_mul_f32_e32 v114, 0x4b800000, v117
	v_cndmask_b32_e32 v117, v117, v114, vcc
	v_rsq_f32_e32 v117, v117
	s_nop 0
	v_mul_f32_e32 v114, 0x45800000, v117
	v_cndmask_b32_e32 v117, v117, v114, vcc
	v_mul_f32_e32 v16, v16, v117
	v_mul_f32_e32 v16, v96, v16
	v_add_f32_e32 v64, 1.0, v64
	v_fma_f32 v16, v16, v64, v80
	v_mul_f32_e32 v17, v17, v117
	v_mul_f32_e32 v17, v97, v17
	v_add_f32_e32 v65, 1.0, v65
	v_fma_f32 v17, v17, v65, v81
	v_mul_f32_e32 v18, v18, v117
	v_mul_f32_e32 v18, v98, v18
	v_add_f32_e32 v66, 1.0, v66
	v_fma_f32 v18, v18, v66, v82
	v_mul_f32_e32 v19, v19, v117
	v_mul_f32_e32 v19, v99, v19
	v_add_f32_e32 v67, 1.0, v67
	v_fma_f32 v19, v19, v67, v83
	v_mul_f32_e32 v20, v20, v117
	v_mul_f32_e32 v20, v100, v20
	v_add_f32_e32 v68, 1.0, v68
	v_fma_f32 v20, v20, v68, v84
	v_mul_f32_e32 v21, v21, v117
	v_mul_f32_e32 v21, v101, v21
	v_add_f32_e32 v69, 1.0, v69
	v_fma_f32 v21, v21, v69, v85
	v_mul_f32_e32 v22, v22, v117
	v_mul_f32_e32 v22, v102, v22
	v_add_f32_e32 v70, 1.0, v70
	v_fma_f32 v22, v22, v70, v86
	v_mul_f32_e32 v23, v23, v117
	v_mul_f32_e32 v23, v103, v23
	v_add_f32_e32 v71, 1.0, v71
	v_fma_f32 v23, v23, v71, v87
	v_mul_f32_e32 v24, v24, v117
	v_mul_f32_e32 v24, v104, v24
	v_add_f32_e32 v72, 1.0, v72
	v_fma_f32 v24, v24, v72, v88
	v_mul_f32_e32 v25, v25, v117
	v_mul_f32_e32 v25, v105, v25
	v_add_f32_e32 v73, 1.0, v73
	v_fma_f32 v25, v25, v73, v89
	v_mul_f32_e32 v26, v26, v117
	v_mul_f32_e32 v26, v106, v26
	v_add_f32_e32 v74, 1.0, v74
	v_fma_f32 v26, v26, v74, v90
	v_mul_f32_e32 v27, v27, v117
	v_mul_f32_e32 v27, v107, v27
	v_add_f32_e32 v75, 1.0, v75
	v_fma_f32 v27, v27, v75, v91
	v_mul_f32_e32 v28, v28, v117
	v_mul_f32_e32 v28, v108, v28
	v_add_f32_e32 v76, 1.0, v76
	v_fma_f32 v28, v28, v76, v92
	v_mul_f32_e32 v29, v29, v117
	v_mul_f32_e32 v29, v109, v29
	v_add_f32_e32 v77, 1.0, v77
	v_fma_f32 v29, v29, v77, v93
	v_mul_f32_e32 v30, v30, v117
	v_mul_f32_e32 v30, v110, v30
	v_add_f32_e32 v78, 1.0, v78
	v_fma_f32 v30, v30, v78, v94
	v_mul_f32_e32 v31, v31, v117
	v_mul_f32_e32 v31, v111, v31
	v_add_f32_e32 v79, 1.0, v79
	v_fma_f32 v31, v31, v79, v95
	v_cvt_pk_bf16_f32 v16, v16, v17
	v_cvt_pk_bf16_f32 v17, v18, v19
	global_store_dwordx2 v116, v[16:17], s[8:9]
	v_cvt_pk_bf16_f32 v20, v20, v21
	v_cvt_pk_bf16_f32 v21, v22, v23
	global_store_dwordx2 v116, v[20:21], s[8:9] offset:512
	v_cvt_pk_bf16_f32 v24, v24, v25
	v_cvt_pk_bf16_f32 v25, v26, v27
	global_store_dwordx2 v116, v[24:25], s[8:9] offset:1024
	v_cvt_pk_bf16_f32 v28, v28, v29
	v_cvt_pk_bf16_f32 v29, v30, v31
	global_store_dwordx2 v116, v[28:29], s[8:9] offset:1536
	s_add_u32 s8, s8, 0x400000
	s_addc_u32 s9, s9, 0
	s_lshl_b32 s15, s14, 12
	s_add_u32 s0, s64, s15
	s_addc_u32 s1, s65, 0
	s_lshr_b32 s15, s14, s36
	s_add_u32 s15, s15, s16
	s_mul_i32 s15, s15, 0x6000
	s_add_u32 s42, s86, s15
	s_addc_u32 s43, s87, 0
	s_add_u32 s4, s42, 0x4000
	s_addc_u32 s5, s43, 0
	s_add_u32 s6, s42, 0x3000
	s_addc_u32 s7, s43, 0
	global_load_dwordx4 v[16:19], v115, s[0:1]
	global_load_dwordx4 v[20:23], v115, s[0:1] offset:1024
	global_load_dwordx4 v[24:27], v115, s[0:1] offset:2048
	global_load_dwordx4 v[28:31], v115, s[0:1] offset:3072
	global_load_dwordx4 v[64:67], v115, s[4:5]
	global_load_dwordx4 v[68:71], v115, s[4:5] offset:1024
	global_load_dwordx4 v[72:75], v115, s[4:5] offset:2048
	global_load_dwordx4 v[76:79], v115, s[4:5] offset:3072
	global_load_dwordx4 v[80:83], v115, s[6:7]
	global_load_dwordx4 v[84:87], v115, s[6:7] offset:1024
	global_load_dwordx4 v[88:91], v115, s[6:7] offset:2048
	global_load_dwordx4 v[92:95], v115, s[6:7] offset:3072
	s_add_u32 s14, s14, 0x800
	s_add_u32 s44, s44, 1
	s_branch .Lnorm2_loop
; DEV void phase_norm_adaln(const float* __restrict__ X, const float* __restrict__ gvec, const float* __restrict__ mod,
;                           int bg0, int L, int sh_off, int sc_off, u16* __restrict__ H) {
;     ...
;     for (int j = 0; j < RB; ++j) {
;       const int row = row0 + j * stride;
;       if (row < NTOK) {
;         const float rstd = rsqrtf(ss[j] * (1.f / 1024.f) + EPSF);
;         const float* mrow = mod + (long)(bg0 + row / L) * DIN;
; #pragma unroll
;         for (int i = 0; i < 4; ++i) {
;           const int k = lane * 4 + 256 * i;
;           const float4 g = *(const float4*)(gvec + k);
;           const float4 sc = *(const float4*)(mrow + sc_off + k);
;           const float4 sh = *(const float4*)(mrow + sh_off + k);
;           const float o0 = v[j][i].x * rstd * g.x * (1.f + sc.x) + sh.x;
;           const float o1 = v[j][i].y * rstd * g.y * (1.f + sc.y) + sh.y;
;           const float o2 = v[j][i].z * rstd * g.z * (1.f + sc.z) + sh.z;
;           const float o3 = v[j][i].w * rstd * g.w * (1.f + sc.w) + sh.w;
;           *(uint2*)(H + (long)row * D + k) = make_uint2(pack2(o0, o1), pack2(o2, o3));
;         }
;       }
;     }
.Lnorm2_tail:
	s_waitcnt vmcnt(4)
	v_mul_f32_e32 v112, v16, v16
	v_fmac_f32_e32 v112, v17, v17
	v_fmac_f32_e32 v112, v18, v18
	v_fmac_f32_e32 v112, v19, v19
	v_fmac_f32_e32 v112, v20, v20
	v_fmac_f32_e32 v112, v21, v21
	v_fmac_f32_e32 v112, v22, v22
	v_fmac_f32_e32 v112, v23, v23
	v_fmac_f32_e32 v112, v24, v24
	v_fmac_f32_e32 v112, v25, v25
	v_fmac_f32_e32 v112, v26, v26
	v_fmac_f32_e32 v112, v27, v27
	v_fmac_f32_e32 v112, v28, v28
	v_fmac_f32_e32 v112, v29, v29
	v_fmac_f32_e32 v112, v30, v30
	v_fmac_f32_e32 v112, v31, v31
	s_nop 1
	v_add_f32_dpp v112, v112, v112 quad_perm:[1,0,3,2] row_mask:0xf bank_mask:0xf
	s_nop 1
	v_add_f32_dpp v112, v112, v112 quad_perm:[2,3,0,1] row_mask:0xf bank_mask:0xf
	s_nop 1
	v_add_f32_dpp v112, v112, v112 row_half_mirror row_mask:0xf bank_mask:0xf
	s_nop 1
	v_add_f32_dpp v112, v112, v112 row_mirror row_mask:0xf bank_mask:0xf
	s_nop 1
	v_add_f32_dpp v112, v112, v112 row_bcast:15 row_mask:0xa bank_mask:0xf
	s_nop 1
	v_add_f32_dpp v112, v112, v112 row_bcast:31 row_mask:0xc bank_mask:0xf
	s_nop 1
	v_readlane_b32 s15, v112, 63
	v_mov_b32_e32 v113, 0x3a800000
	s_nop 1
	v_fma_f32 v117, s15, v113, v212
	v_cmp_gt_f32_e32 vcc, s25, v117
	v_mul_f32_e32 v114, 0x4b800000, v117
	v_cndmask_b32_e32 v117, v117, v114, vcc
	v_rsq_f32_e32 v117, v117
	s_nop 0
	v_mul_f32_e32 v114, 0x45800000, v117
	v_cndmask_b32_e32 v117, v117, v114, vcc
	v_mul_f32_e32 v16, v16, v117
	v_mul_f32_e32 v16, v96, v16
	v_add_f32_e32 v64, 1.0, v64
	v_fma_f32 v16, v16, v64, v80
	v_mul_f32_e32 v17, v17, v117
	v_mul_f32_e32 v17, v97, v17
	v_add_f32_e32 v65, 1.0, v65
	v_fma_f32 v17, v17, v65, v81
	v_mul_f32_e32 v18, v18, v117
	v_mul_f32_e32 v18, v98, v18
	v_add_f32_e32 v66, 1.0, v66
	v_fma_f32 v18, v18, v66, v82
	v_mul_f32_e32 v19, v19, v117
	v_mul_f32_e32 v19, v99, v19
	v_add_f32_e32 v67, 1.0, v67
	v_fma_f32 v19, v19, v67, v83
	v_mul_f32_e32 v20, v20, v117
	v_mul_f32_e32 v20, v100, v20
	v_add_f32_e32 v68, 1.0, v68
	v_fma_f32 v20, v20, v68, v84
	v_mul_f32_e32 v21, v21, v117
	v_mul_f32_e32 v21, v101, v21
	v_add_f32_e32 v69, 1.0, v69
	v_fma_f32 v21, v21, v69, v85
	v_mul_f32_e32 v22, v22, v117
	v_mul_f32_e32 v22, v102, v22
	v_add_f32_e32 v70, 1.0, v70
	v_fma_f32 v22, v22, v70, v86
	v_mul_f32_e32 v23, v23, v117
	v_mul_f32_e32 v23, v103, v23
	v_add_f32_e32 v71, 1.0, v71
	v_fma_f32 v23, v23, v71, v87
	v_mul_f32_e32 v24, v24, v117
	v_mul_f32_e32 v24, v104, v24
	v_add_f32_e32 v72, 1.0, v72
	v_fma_f32 v24, v24, v72, v88
	v_mul_f32_e32 v25, v25, v117
	v_mul_f32_e32 v25, v105, v25
	v_add_f32_e32 v73, 1.0, v73
	v_fma_f32 v25, v25, v73, v89
	v_mul_f32_e32 v26, v26, v117
	v_mul_f32_e32 v26, v106, v26
	v_add_f32_e32 v74, 1.0, v74
	v_fma_f32 v26, v26, v74, v90
	v_mul_f32_e32 v27, v27, v117
	v_mul_f32_e32 v27, v107, v27
	v_add_f32_e32 v75, 1.0, v75
	v_fma_f32 v27, v27, v75, v91
	v_mul_f32_e32 v28, v28, v117
	v_mul_f32_e32 v28, v108, v28
	v_add_f32_e32 v76, 1.0, v76
	v_fma_f32 v28, v28, v76, v92
	v_mul_f32_e32 v29, v29, v117
	v_mul_f32_e32 v29, v109, v29
	v_add_f32_e32 v77, 1.0, v77
	v_fma_f32 v29, v29, v77, v93
	v_mul_f32_e32 v30, v30, v117
	v_mul_f32_e32 v30, v110, v30
	v_add_f32_e32 v78, 1.0, v78
	v_fma_f32 v30, v30, v78, v94
	v_mul_f32_e32 v31, v31, v117
	v_mul_f32_e32 v31, v111, v31
	v_add_f32_e32 v79, 1.0, v79
	v_fma_f32 v31, v31, v79, v95
	v_cvt_pk_bf16_f32 v16, v16, v17
	v_cvt_pk_bf16_f32 v17, v18, v19
	global_store_dwordx2 v116, v[16:17], s[8:9]
	v_cvt_pk_bf16_f32 v20, v20, v21
	v_cvt_pk_bf16_f32 v21, v22, v23
	global_store_dwordx2 v116, v[20:21], s[8:9] offset:512
	v_cvt_pk_bf16_f32 v24, v24, v25
	v_cvt_pk_bf16_f32 v25, v26, v27
	global_store_dwordx2 v116, v[24:25], s[8:9] offset:1024
	v_cvt_pk_bf16_f32 v28, v28, v29
	v_cvt_pk_bf16_f32 v29, v30, v31
	global_store_dwordx2 v116, v[28:29], s[8:9] offset:1536
